# phase 1 (layer-0 rmsnorm + adaLN modulate) hand-written: next step's row loads in flight during the current step, modulation vectors requested before the wave reduction, counted vmcnt; rstd by v_rsq_f
# speedup vs baseline: 1.0025x; 1.0025x over previous
.LBB0_121:
	s_cmp_lt_i32 s40, 2
	s_cselect_b64 s[10:11], -1, 0
	s_and_b64 s[0:1], s[0:1], s[10:11]
	s_andn2_b64 vcc, exec, s[0:1]
	s_cbranch_vccnz .LBB0_133
	v_mov_b32_e32 v9, 0
	global_load_dwordx2 v[160:161], v9, s[96:97] sc0
	global_load_dwordx2 v[162:163], v9, s[96:97] offset:8 sc0
	global_load_dwordx2 v[164:165], v9, s[96:97] offset:64 sc0
	v_mbcnt_lo_u32_b32 v0, -1, 0
	v_mbcnt_hi_u32_b32 v0, -1, v0
	v_lshlrev_b32_e32 v1, 4, v0
	v_lshlrev_b32_e32 v8, 3, v0
	v_xor_b32_e32 v2, 1, v0
	v_lshlrev_b32_e32 v2, 2, v2
	v_xor_b32_e32 v3, 2, v0
	v_lshlrev_b32_e32 v3, 2, v3
	v_xor_b32_e32 v4, 4, v0
	v_lshlrev_b32_e32 v4, 2, v4
	v_xor_b32_e32 v5, 8, v0
	v_lshlrev_b32_e32 v5, 2, v5
	v_xor_b32_e32 v6, 16, v0
	v_lshlrev_b32_e32 v6, 2, v6
	v_xor_b32_e32 v7, 32, v0
	v_lshlrev_b32_e32 v7, 2, v7
	s_waitcnt vmcnt(0)
	v_readfirstlane_b32 s24, v160
	v_readfirstlane_b32 s25, v161
	v_readfirstlane_b32 s26, v162
	v_readfirstlane_b32 s27, v163
	v_readfirstlane_b32 s28, v164
	v_readfirstlane_b32 s29, v165
	s_nop 4
	global_load_dwordx4 v[10:13], v1, s[28:29]
	global_load_dwordx4 v[14:17], v1, s[28:29] offset:1024
	global_load_dwordx4 v[18:21], v1, s[28:29] offset:2048
	global_load_dwordx4 v[22:25], v1, s[28:29] offset:3072
	s_mov_b32 s9, s8
	s_lshl_b32 s9, s9, 12
	s_add_u32 s12, s24, s9
	s_addc_u32 s13, s25, 0
	s_add_i32 s9, s8, 0x800
	s_lshl_b32 s9, s9, 12
	s_add_u32 s14, s24, s9
	s_addc_u32 s15, s25, 0
	global_load_dwordx4 v[32:35], v1, s[12:13]
	global_load_dwordx4 v[36:39], v1, s[12:13] offset:1024
	global_load_dwordx4 v[40:43], v1, s[12:13] offset:2048
	global_load_dwordx4 v[44:47], v1, s[12:13] offset:3072
	global_load_dwordx4 v[48:51], v1, s[14:15]
	global_load_dwordx4 v[52:55], v1, s[14:15] offset:1024
	global_load_dwordx4 v[56:59], v1, s[14:15] offset:2048
	global_load_dwordx4 v[60:63], v1, s[14:15] offset:3072
	s_add_u32 s16, s54, 0x18000
	s_addc_u32 s17, s55, 0
	global_load_dwordx4 v[128:131], v1, s[16:17]
	global_load_dwordx4 v[132:135], v1, s[16:17] offset:1024
	global_load_dwordx4 v[136:139], v1, s[16:17] offset:2048
	global_load_dwordx4 v[140:143], v1, s[16:17] offset:3072
	s_add_u32 s16, s16, 0x1000
	s_addc_u32 s17, s17, 0
	global_load_dwordx4 v[96:99], v1, s[16:17]
	global_load_dwordx4 v[100:103], v1, s[16:17] offset:1024
	global_load_dwordx4 v[104:107], v1, s[16:17] offset:2048
	global_load_dwordx4 v[108:111], v1, s[16:17] offset:3072
	s_add_u32 s16, s54, 0x18000
	s_addc_u32 s17, s55, 0
	global_load_dwordx4 v[144:147], v1, s[16:17]
	global_load_dwordx4 v[148:151], v1, s[16:17] offset:1024
	global_load_dwordx4 v[152:155], v1, s[16:17] offset:2048
	global_load_dwordx4 v[156:159], v1, s[16:17] offset:3072
	s_add_u32 s16, s16, 0x1000
	s_addc_u32 s17, s17, 0
	global_load_dwordx4 v[112:115], v1, s[16:17]
	global_load_dwordx4 v[116:119], v1, s[16:17] offset:1024
	global_load_dwordx4 v[120:123], v1, s[16:17] offset:2048
	global_load_dwordx4 v[124:127], v1, s[16:17] offset:3072
	s_mov_b32 s9, s8
	s_lshl_b32 s9, s9, 12
	s_add_u32 s12, s26, s9
	s_addc_u32 s13, s27, 0
	s_add_i32 s9, s8, 0x800
	s_lshl_b32 s9, s9, 12
	s_add_u32 s14, s26, s9
	s_addc_u32 s15, s27, 0
	global_load_dwordx4 v[64:67], v1, s[12:13]
	global_load_dwordx4 v[68:71], v1, s[12:13] offset:1024
	global_load_dwordx4 v[72:75], v1, s[12:13] offset:2048
	global_load_dwordx4 v[76:79], v1, s[12:13] offset:3072
	global_load_dwordx4 v[80:83], v1, s[14:15]
	global_load_dwordx4 v[84:87], v1, s[14:15] offset:1024
	global_load_dwordx4 v[88:91], v1, s[14:15] offset:2048
	global_load_dwordx4 v[92:95], v1, s[14:15] offset:3072
	s_waitcnt vmcnt(24)
	v_mul_f32_e32 v166, v32, v32
	v_fmac_f32_e32 v166, v33, v33
	v_mul_f32_e32 v167, v34, v34
	v_fmac_f32_e32 v167, v35, v35
	v_add_f32_e32 v160, v166, v167
	v_mul_f32_e32 v166, v36, v36
	v_fmac_f32_e32 v166, v37, v37
	v_mul_f32_e32 v167, v38, v38
	v_fmac_f32_e32 v167, v39, v39
	v_add_f32_e32 v166, v166, v167
	v_add_f32_e32 v160, v160, v166
	v_mul_f32_e32 v166, v40, v40
	v_fmac_f32_e32 v166, v41, v41
	v_mul_f32_e32 v167, v42, v42
	v_fmac_f32_e32 v167, v43, v43
	v_add_f32_e32 v166, v166, v167
	v_add_f32_e32 v160, v160, v166
	v_mul_f32_e32 v166, v44, v44
	v_fmac_f32_e32 v166, v45, v45
	v_mul_f32_e32 v167, v46, v46
	v_fmac_f32_e32 v167, v47, v47
	v_add_f32_e32 v166, v166, v167
	v_add_f32_e32 v160, v160, v166
	v_mul_f32_e32 v166, v48, v48
	v_fmac_f32_e32 v166, v49, v49
	v_mul_f32_e32 v167, v50, v50
	v_fmac_f32_e32 v167, v51, v51
	v_add_f32_e32 v161, v166, v167
	v_mul_f32_e32 v166, v52, v52
	v_fmac_f32_e32 v166, v53, v53
	v_mul_f32_e32 v167, v54, v54
	v_fmac_f32_e32 v167, v55, v55
	v_add_f32_e32 v166, v166, v167
	v_add_f32_e32 v161, v161, v166
	v_mul_f32_e32 v166, v56, v56
	v_fmac_f32_e32 v166, v57, v57
	v_mul_f32_e32 v167, v58, v58
	v_fmac_f32_e32 v167, v59, v59
	v_add_f32_e32 v166, v166, v167
	v_add_f32_e32 v161, v161, v166
	v_mul_f32_e32 v166, v60, v60
	v_fmac_f32_e32 v166, v61, v61
	v_mul_f32_e32 v167, v62, v62
	v_fmac_f32_e32 v167, v63, v63
	v_add_f32_e32 v166, v166, v167
	v_add_f32_e32 v161, v161, v166
	ds_bpermute_b32 v164, v2, v160
	ds_bpermute_b32 v165, v2, v161
	s_waitcnt lgkmcnt(0)
	v_add_f32_e32 v160, v160, v164
	v_add_f32_e32 v161, v161, v165
	ds_bpermute_b32 v164, v3, v160
	ds_bpermute_b32 v165, v3, v161
	s_waitcnt lgkmcnt(0)
	v_add_f32_e32 v160, v160, v164
	v_add_f32_e32 v161, v161, v165
	ds_bpermute_b32 v164, v4, v160
	ds_bpermute_b32 v165, v4, v161
	s_waitcnt lgkmcnt(0)
	v_add_f32_e32 v160, v160, v164
	v_add_f32_e32 v161, v161, v165
	ds_bpermute_b32 v164, v5, v160
	ds_bpermute_b32 v165, v5, v161
	s_waitcnt lgkmcnt(0)
	v_add_f32_e32 v160, v160, v164
	v_add_f32_e32 v161, v161, v165
	ds_bpermute_b32 v164, v6, v160
	ds_bpermute_b32 v165, v6, v161
	s_waitcnt lgkmcnt(0)
	v_add_f32_e32 v160, v160, v164
	v_add_f32_e32 v161, v161, v165
	ds_bpermute_b32 v164, v7, v160
	ds_bpermute_b32 v165, v7, v161
	s_waitcnt lgkmcnt(0)
	v_add_f32_e32 v160, v160, v164
	v_add_f32_e32 v161, v161, v165
	v_mul_f32_e32 v162, 0x3a800000, v160
	v_add_f32_e32 v162, 0x358637bd, v162
	v_mul_f32_e32 v163, 0x3a800000, v161
	v_add_f32_e32 v163, 0x358637bd, v163
	v_rsq_f32_e32 v162, v162
	v_rsq_f32_e32 v163, v163
	s_waitcnt vmcnt(8)
	s_mov_b32 s9, s8
	s_lshl_b32 s9, s9, 11
	s_add_u32 s0, s54, s9
	s_addc_u32 s1, s55, 0
	s_add_u32 s4, s0, 0xda00000
	s_addc_u32 s5, s1, 0
	s_add_u32 s0, s0, 0x4200000
	s_addc_u32 s1, s1, 0
	v_mul_f32_e32 v168, v32, v162
	v_mul_f32_e32 v168, v168, v10
	v_add_f32_e32 v172, 1.0, v96
	v_fma_f32 v168, v168, v172, v128
	v_mul_f32_e32 v169, v33, v162
	v_mul_f32_e32 v169, v169, v11
	v_add_f32_e32 v173, 1.0, v97
	v_fma_f32 v169, v169, v173, v129
	v_mul_f32_e32 v170, v34, v162
	v_mul_f32_e32 v170, v170, v12
	v_add_f32_e32 v174, 1.0, v98
	v_fma_f32 v170, v170, v174, v130
	v_mul_f32_e32 v171, v35, v162
	v_mul_f32_e32 v171, v171, v13
	v_add_f32_e32 v175, 1.0, v99
	v_fma_f32 v171, v171, v175, v131
	v_cvt_pk_bf16_f32 v176, v168, v169
	v_cvt_pk_bf16_f32 v177, v170, v171
	v_cvt_pk_bf16_f32 v178, v32, v33
	v_cvt_pk_bf16_f32 v179, v34, v35
	global_store_dwordx2 v8, v[176:177], s[0:1]
	global_store_dwordx2 v8, v[178:179], s[4:5]
	v_mul_f32_e32 v168, v36, v162
	v_mul_f32_e32 v168, v168, v14
	v_add_f32_e32 v172, 1.0, v100
	v_fma_f32 v168, v168, v172, v132
	v_mul_f32_e32 v169, v37, v162
	v_mul_f32_e32 v169, v169, v15
	v_add_f32_e32 v173, 1.0, v101
	v_fma_f32 v169, v169, v173, v133
	v_mul_f32_e32 v170, v38, v162
	v_mul_f32_e32 v170, v170, v16
	v_add_f32_e32 v174, 1.0, v102
	v_fma_f32 v170, v170, v174, v134
	v_mul_f32_e32 v171, v39, v162
	v_mul_f32_e32 v171, v171, v17
	v_add_f32_e32 v175, 1.0, v103
	v_fma_f32 v171, v171, v175, v135
	v_cvt_pk_bf16_f32 v180, v168, v169
	v_cvt_pk_bf16_f32 v181, v170, v171
	v_cvt_pk_bf16_f32 v182, v36, v37
	v_cvt_pk_bf16_f32 v183, v38, v39
	global_store_dwordx2 v8, v[180:181], s[0:1] offset:512
	global_store_dwordx2 v8, v[182:183], s[4:5] offset:512
	v_mul_f32_e32 v168, v40, v162
	v_mul_f32_e32 v168, v168, v18
	v_add_f32_e32 v172, 1.0, v104
	v_fma_f32 v168, v168, v172, v136
	v_mul_f32_e32 v169, v41, v162
	v_mul_f32_e32 v169, v169, v19
	v_add_f32_e32 v173, 1.0, v105
	v_fma_f32 v169, v169, v173, v137
	v_mul_f32_e32 v170, v42, v162
	v_mul_f32_e32 v170, v170, v20
	v_add_f32_e32 v174, 1.0, v106
	v_fma_f32 v170, v170, v174, v138
	v_mul_f32_e32 v171, v43, v162
	v_mul_f32_e32 v171, v171, v21
	v_add_f32_e32 v175, 1.0, v107
	v_fma_f32 v171, v171, v175, v139
	v_cvt_pk_bf16_f32 v184, v168, v169
	v_cvt_pk_bf16_f32 v185, v170, v171
	v_cvt_pk_bf16_f32 v186, v40, v41
	v_cvt_pk_bf16_f32 v187, v42, v43
	global_store_dwordx2 v8, v[184:185], s[0:1] offset:1024
	global_store_dwordx2 v8, v[186:187], s[4:5] offset:1024
	v_mul_f32_e32 v168, v44, v162
	v_mul_f32_e32 v168, v168, v22
	v_add_f32_e32 v172, 1.0, v108
	v_fma_f32 v168, v168, v172, v140
	v_mul_f32_e32 v169, v45, v162
	v_mul_f32_e32 v169, v169, v23
	v_add_f32_e32 v173, 1.0, v109
	v_fma_f32 v169, v169, v173, v141
	v_mul_f32_e32 v170, v46, v162
	v_mul_f32_e32 v170, v170, v24
	v_add_f32_e32 v174, 1.0, v110
	v_fma_f32 v170, v170, v174, v142
	v_mul_f32_e32 v171, v47, v162
	v_mul_f32_e32 v171, v171, v25
	v_add_f32_e32 v175, 1.0, v111
	v_fma_f32 v171, v171, v175, v143
	v_cvt_pk_bf16_f32 v188, v168, v169
	v_cvt_pk_bf16_f32 v189, v170, v171
	v_cvt_pk_bf16_f32 v190, v44, v45
	v_cvt_pk_bf16_f32 v191, v46, v47
	global_store_dwordx2 v8, v[188:189], s[0:1] offset:1536
	global_store_dwordx2 v8, v[190:191], s[4:5] offset:1536
	s_add_i32 s9, s8, 0x800
	s_lshl_b32 s9, s9, 11
	s_add_u32 s0, s54, s9
	s_addc_u32 s1, s55, 0
	s_add_u32 s4, s0, 0xda00000
	s_addc_u32 s5, s1, 0
	s_add_u32 s0, s0, 0x4200000
	s_addc_u32 s1, s1, 0
	v_mul_f32_e32 v168, v48, v163
	v_mul_f32_e32 v168, v168, v10
	v_add_f32_e32 v172, 1.0, v112
	v_fma_f32 v168, v168, v172, v144
	v_mul_f32_e32 v169, v49, v163
	v_mul_f32_e32 v169, v169, v11
	v_add_f32_e32 v173, 1.0, v113
	v_fma_f32 v169, v169, v173, v145
	v_mul_f32_e32 v170, v50, v163
	v_mul_f32_e32 v170, v170, v12
	v_add_f32_e32 v174, 1.0, v114
	v_fma_f32 v170, v170, v174, v146
	v_mul_f32_e32 v171, v51, v163
	v_mul_f32_e32 v171, v171, v13
	v_add_f32_e32 v175, 1.0, v115
	v_fma_f32 v171, v171, v175, v147
	v_cvt_pk_bf16_f32 v176, v168, v169
	v_cvt_pk_bf16_f32 v177, v170, v171
	v_cvt_pk_bf16_f32 v178, v48, v49
	v_cvt_pk_bf16_f32 v179, v50, v51
	global_store_dwordx2 v8, v[176:177], s[0:1]
	global_store_dwordx2 v8, v[178:179], s[4:5]
	v_mul_f32_e32 v168, v52, v163
	v_mul_f32_e32 v168, v168, v14
	v_add_f32_e32 v172, 1.0, v116
	v_fma_f32 v168, v168, v172, v148
	v_mul_f32_e32 v169, v53, v163
	v_mul_f32_e32 v169, v169, v15
	v_add_f32_e32 v173, 1.0, v117
	v_fma_f32 v169, v169, v173, v149
	v_mul_f32_e32 v170, v54, v163
	v_mul_f32_e32 v170, v170, v16
	v_add_f32_e32 v174, 1.0, v118
	v_fma_f32 v170, v170, v174, v150
	v_mul_f32_e32 v171, v55, v163
	v_mul_f32_e32 v171, v171, v17
	v_add_f32_e32 v175, 1.0, v119
	v_fma_f32 v171, v171, v175, v151
	v_cvt_pk_bf16_f32 v180, v168, v169
	v_cvt_pk_bf16_f32 v181, v170, v171
	v_cvt_pk_bf16_f32 v182, v52, v53
	v_cvt_pk_bf16_f32 v183, v54, v55
	global_store_dwordx2 v8, v[180:181], s[0:1] offset:512
	global_store_dwordx2 v8, v[182:183], s[4:5] offset:512
	v_mul_f32_e32 v168, v56, v163
	v_mul_f32_e32 v168, v168, v18
	v_add_f32_e32 v172, 1.0, v120
	v_fma_f32 v168, v168, v172, v152
	v_mul_f32_e32 v169, v57, v163
	v_mul_f32_e32 v169, v169, v19
	v_add_f32_e32 v173, 1.0, v121
	v_fma_f32 v169, v169, v173, v153
	v_mul_f32_e32 v170, v58, v163
	v_mul_f32_e32 v170, v170, v20
	v_add_f32_e32 v174, 1.0, v122
	v_fma_f32 v170, v170, v174, v154
	v_mul_f32_e32 v171, v59, v163
	v_mul_f32_e32 v171, v171, v21
	v_add_f32_e32 v175, 1.0, v123
	v_fma_f32 v171, v171, v175, v155
	v_cvt_pk_bf16_f32 v184, v168, v169
	v_cvt_pk_bf16_f32 v185, v170, v171
	v_cvt_pk_bf16_f32 v186, v56, v57
	v_cvt_pk_bf16_f32 v187, v58, v59
	global_store_dwordx2 v8, v[184:185], s[0:1] offset:1024
	global_store_dwordx2 v8, v[186:187], s[4:5] offset:1024
	v_mul_f32_e32 v168, v60, v163
	v_mul_f32_e32 v168, v168, v22
	v_add_f32_e32 v172, 1.0, v124
	v_fma_f32 v168, v168, v172, v156
	v_mul_f32_e32 v169, v61, v163
	v_mul_f32_e32 v169, v169, v23
	v_add_f32_e32 v173, 1.0, v125
	v_fma_f32 v169, v169, v173, v157
	v_mul_f32_e32 v170, v62, v163
	v_mul_f32_e32 v170, v170, v24
	v_add_f32_e32 v174, 1.0, v126
	v_fma_f32 v170, v170, v174, v158
	v_mul_f32_e32 v171, v63, v163
	v_mul_f32_e32 v171, v171, v25
	v_add_f32_e32 v175, 1.0, v127
	v_fma_f32 v171, v171, v175, v159
	v_cvt_pk_bf16_f32 v188, v168, v169
	v_cvt_pk_bf16_f32 v189, v170, v171
	v_cvt_pk_bf16_f32 v190, v60, v61
	v_cvt_pk_bf16_f32 v191, v62, v63
	global_store_dwordx2 v8, v[188:189], s[0:1] offset:1536
	global_store_dwordx2 v8, v[190:191], s[4:5] offset:1536
	s_add_u32 s16, s54, 0x0
	s_addc_u32 s17, s55, 0
	global_load_dwordx4 v[128:131], v1, s[16:17]
	global_load_dwordx4 v[132:135], v1, s[16:17] offset:1024
	global_load_dwordx4 v[136:139], v1, s[16:17] offset:2048
	global_load_dwordx4 v[140:143], v1, s[16:17] offset:3072
	s_add_u32 s16, s16, 0x1000
	s_addc_u32 s17, s17, 0
	global_load_dwordx4 v[96:99], v1, s[16:17]
	global_load_dwordx4 v[100:103], v1, s[16:17] offset:1024
	global_load_dwordx4 v[104:107], v1, s[16:17] offset:2048
	global_load_dwordx4 v[108:111], v1, s[16:17] offset:3072
	s_add_u32 s16, s54, 0x6000
	s_addc_u32 s17, s55, 0
	global_load_dwordx4 v[144:147], v1, s[16:17]
	global_load_dwordx4 v[148:151], v1, s[16:17] offset:1024
	global_load_dwordx4 v[152:155], v1, s[16:17] offset:2048
	global_load_dwordx4 v[156:159], v1, s[16:17] offset:3072
	s_add_u32 s16, s16, 0x1000
	s_addc_u32 s17, s17, 0
	global_load_dwordx4 v[112:115], v1, s[16:17]
	global_load_dwordx4 v[116:119], v1, s[16:17] offset:1024
	global_load_dwordx4 v[120:123], v1, s[16:17] offset:2048
	global_load_dwordx4 v[124:127], v1, s[16:17] offset:3072
	s_add_i32 s9, s8, 0x1000
	s_lshl_b32 s9, s9, 12
	s_add_u32 s12, s26, s9
	s_addc_u32 s13, s27, 0
	s_add_i32 s9, s8, 0x1800
	s_lshl_b32 s9, s9, 12
	s_add_u32 s14, s26, s9
	s_addc_u32 s15, s27, 0
	global_load_dwordx4 v[32:35], v1, s[12:13]
	global_load_dwordx4 v[36:39], v1, s[12:13] offset:1024
	global_load_dwordx4 v[40:43], v1, s[12:13] offset:2048
	global_load_dwordx4 v[44:47], v1, s[12:13] offset:3072
	global_load_dwordx4 v[48:51], v1, s[14:15]
	global_load_dwordx4 v[52:55], v1, s[14:15] offset:1024
	global_load_dwordx4 v[56:59], v1, s[14:15] offset:2048
	global_load_dwordx4 v[60:63], v1, s[14:15] offset:3072
	s_waitcnt vmcnt(40)
	v_mul_f32_e32 v166, v64, v64
	v_fmac_f32_e32 v166, v65, v65
	v_mul_f32_e32 v167, v66, v66
	v_fmac_f32_e32 v167, v67, v67
	v_add_f32_e32 v160, v166, v167
	v_mul_f32_e32 v166, v68, v68
	v_fmac_f32_e32 v166, v69, v69
	v_mul_f32_e32 v167, v70, v70
	v_fmac_f32_e32 v167, v71, v71
	v_add_f32_e32 v166, v166, v167
	v_add_f32_e32 v160, v160, v166
	v_mul_f32_e32 v166, v72, v72
	v_fmac_f32_e32 v166, v73, v73
	v_mul_f32_e32 v167, v74, v74
	v_fmac_f32_e32 v167, v75, v75
	v_add_f32_e32 v166, v166, v167
	v_add_f32_e32 v160, v160, v166
	v_mul_f32_e32 v166, v76, v76
	v_fmac_f32_e32 v166, v77, v77
	v_mul_f32_e32 v167, v78, v78
	v_fmac_f32_e32 v167, v79, v79
	v_add_f32_e32 v166, v166, v167
	v_add_f32_e32 v160, v160, v166
	v_mul_f32_e32 v166, v80, v80
	v_fmac_f32_e32 v166, v81, v81
	v_mul_f32_e32 v167, v82, v82
	v_fmac_f32_e32 v167, v83, v83
	v_add_f32_e32 v161, v166, v167
	v_mul_f32_e32 v166, v84, v84
	v_fmac_f32_e32 v166, v85, v85
	v_mul_f32_e32 v167, v86, v86
	v_fmac_f32_e32 v167, v87, v87
	v_add_f32_e32 v166, v166, v167
	v_add_f32_e32 v161, v161, v166
	v_mul_f32_e32 v166, v88, v88
	v_fmac_f32_e32 v166, v89, v89
	v_mul_f32_e32 v167, v90, v90
	v_fmac_f32_e32 v167, v91, v91
	v_add_f32_e32 v166, v166, v167
	v_add_f32_e32 v161, v161, v166
	v_mul_f32_e32 v166, v92, v92
	v_fmac_f32_e32 v166, v93, v93
	v_mul_f32_e32 v167, v94, v94
	v_fmac_f32_e32 v167, v95, v95
	v_add_f32_e32 v166, v166, v167
	v_add_f32_e32 v161, v161, v166
	ds_bpermute_b32 v164, v2, v160
	ds_bpermute_b32 v165, v2, v161
	s_waitcnt lgkmcnt(0)
	v_add_f32_e32 v160, v160, v164
	v_add_f32_e32 v161, v161, v165
	ds_bpermute_b32 v164, v3, v160
	ds_bpermute_b32 v165, v3, v161
	s_waitcnt lgkmcnt(0)
	v_add_f32_e32 v160, v160, v164
	v_add_f32_e32 v161, v161, v165
	ds_bpermute_b32 v164, v4, v160
	ds_bpermute_b32 v165, v4, v161
	s_waitcnt lgkmcnt(0)
	v_add_f32_e32 v160, v160, v164
	v_add_f32_e32 v161, v161, v165
	ds_bpermute_b32 v164, v5, v160
	ds_bpermute_b32 v165, v5, v161
	s_waitcnt lgkmcnt(0)
	v_add_f32_e32 v160, v160, v164
	v_add_f32_e32 v161, v161, v165
	ds_bpermute_b32 v164, v6, v160
	ds_bpermute_b32 v165, v6, v161
	s_waitcnt lgkmcnt(0)
	v_add_f32_e32 v160, v160, v164
	v_add_f32_e32 v161, v161, v165
	ds_bpermute_b32 v164, v7, v160
	ds_bpermute_b32 v165, v7, v161
	s_waitcnt lgkmcnt(0)
	v_add_f32_e32 v160, v160, v164
	v_add_f32_e32 v161, v161, v165
	v_mul_f32_e32 v162, 0x3a800000, v160
	v_add_f32_e32 v162, 0x358637bd, v162
	v_mul_f32_e32 v163, 0x3a800000, v161
	v_add_f32_e32 v163, 0x358637bd, v163
	v_rsq_f32_e32 v162, v162
	v_rsq_f32_e32 v163, v163
	s_waitcnt vmcnt(8)
	s_add_i32 s9, s8, 0x1000
	s_lshl_b32 s9, s9, 11
	s_add_u32 s0, s54, s9
	s_addc_u32 s1, s55, 0
	s_add_u32 s4, s0, 0xda00000
	s_addc_u32 s5, s1, 0
	s_add_u32 s0, s0, 0x4200000
	s_addc_u32 s1, s1, 0
	v_mul_f32_e32 v168, v64, v162
	v_mul_f32_e32 v168, v168, v10
	v_add_f32_e32 v172, 1.0, v96
	v_fma_f32 v168, v168, v172, v128
	v_mul_f32_e32 v169, v65, v162
	v_mul_f32_e32 v169, v169, v11
	v_add_f32_e32 v173, 1.0, v97
	v_fma_f32 v169, v169, v173, v129
	v_mul_f32_e32 v170, v66, v162
	v_mul_f32_e32 v170, v170, v12
	v_add_f32_e32 v174, 1.0, v98
	v_fma_f32 v170, v170, v174, v130
	v_mul_f32_e32 v171, v67, v162
	v_mul_f32_e32 v171, v171, v13
	v_add_f32_e32 v175, 1.0, v99
	v_fma_f32 v171, v171, v175, v131
	v_cvt_pk_bf16_f32 v176, v168, v169
	v_cvt_pk_bf16_f32 v177, v170, v171
	v_cvt_pk_bf16_f32 v178, v64, v65
	v_cvt_pk_bf16_f32 v179, v66, v67
	global_store_dwordx2 v8, v[176:177], s[0:1]
	global_store_dwordx2 v8, v[178:179], s[4:5]
	v_mul_f32_e32 v168, v68, v162
	v_mul_f32_e32 v168, v168, v14
	v_add_f32_e32 v172, 1.0, v100
	v_fma_f32 v168, v168, v172, v132
	v_mul_f32_e32 v169, v69, v162
	v_mul_f32_e32 v169, v169, v15
	v_add_f32_e32 v173, 1.0, v101
	v_fma_f32 v169, v169, v173, v133
	v_mul_f32_e32 v170, v70, v162
	v_mul_f32_e32 v170, v170, v16
	v_add_f32_e32 v174, 1.0, v102
	v_fma_f32 v170, v170, v174, v134
	v_mul_f32_e32 v171, v71, v162
	v_mul_f32_e32 v171, v171, v17
	v_add_f32_e32 v175, 1.0, v103
	v_fma_f32 v171, v171, v175, v135
	v_cvt_pk_bf16_f32 v180, v168, v169
	v_cvt_pk_bf16_f32 v181, v170, v171
	v_cvt_pk_bf16_f32 v182, v68, v69
	v_cvt_pk_bf16_f32 v183, v70, v71
	global_store_dwordx2 v8, v[180:181], s[0:1] offset:512
	global_store_dwordx2 v8, v[182:183], s[4:5] offset:512
	v_mul_f32_e32 v168, v72, v162
	v_mul_f32_e32 v168, v168, v18
	v_add_f32_e32 v172, 1.0, v104
	v_fma_f32 v168, v168, v172, v136
	v_mul_f32_e32 v169, v73, v162
	v_mul_f32_e32 v169, v169, v19
	v_add_f32_e32 v173, 1.0, v105
	v_fma_f32 v169, v169, v173, v137
	v_mul_f32_e32 v170, v74, v162
	v_mul_f32_e32 v170, v170, v20
	v_add_f32_e32 v174, 1.0, v106
	v_fma_f32 v170, v170, v174, v138
	v_mul_f32_e32 v171, v75, v162
	v_mul_f32_e32 v171, v171, v21
	v_add_f32_e32 v175, 1.0, v107
	v_fma_f32 v171, v171, v175, v139
	v_cvt_pk_bf16_f32 v184, v168, v169
	v_cvt_pk_bf16_f32 v185, v170, v171
	v_cvt_pk_bf16_f32 v186, v72, v73
	v_cvt_pk_bf16_f32 v187, v74, v75
	global_store_dwordx2 v8, v[184:185], s[0:1] offset:1024
	global_store_dwordx2 v8, v[186:187], s[4:5] offset:1024
	v_mul_f32_e32 v168, v76, v162
	v_mul_f32_e32 v168, v168, v22
	v_add_f32_e32 v172, 1.0, v108
	v_fma_f32 v168, v168, v172, v140
	v_mul_f32_e32 v169, v77, v162
	v_mul_f32_e32 v169, v169, v23
	v_add_f32_e32 v173, 1.0, v109
	v_fma_f32 v169, v169, v173, v141
	v_mul_f32_e32 v170, v78, v162
	v_mul_f32_e32 v170, v170, v24
	v_add_f32_e32 v174, 1.0, v110
	v_fma_f32 v170, v170, v174, v142
	v_mul_f32_e32 v171, v79, v162
	v_mul_f32_e32 v171, v171, v25
	v_add_f32_e32 v175, 1.0, v111
	v_fma_f32 v171, v171, v175, v143
	v_cvt_pk_bf16_f32 v188, v168, v169
	v_cvt_pk_bf16_f32 v189, v170, v171
	v_cvt_pk_bf16_f32 v190, v76, v77
	v_cvt_pk_bf16_f32 v191, v78, v79
	global_store_dwordx2 v8, v[188:189], s[0:1] offset:1536
	global_store_dwordx2 v8, v[190:191], s[4:5] offset:1536
	s_add_i32 s9, s8, 0x1800
	s_lshl_b32 s9, s9, 11
	s_add_u32 s0, s54, s9
	s_addc_u32 s1, s55, 0
	s_add_u32 s4, s0, 0xda00000
	s_addc_u32 s5, s1, 0
	s_add_u32 s0, s0, 0x4200000
	s_addc_u32 s1, s1, 0
	v_mul_f32_e32 v168, v80, v163
	v_mul_f32_e32 v168, v168, v10
	v_add_f32_e32 v172, 1.0, v112
	v_fma_f32 v168, v168, v172, v144
	v_mul_f32_e32 v169, v81, v163
	v_mul_f32_e32 v169, v169, v11
	v_add_f32_e32 v173, 1.0, v113
	v_fma_f32 v169, v169, v173, v145
	v_mul_f32_e32 v170, v82, v163
	v_mul_f32_e32 v170, v170, v12
	v_add_f32_e32 v174, 1.0, v114
	v_fma_f32 v170, v170, v174, v146
	v_mul_f32_e32 v171, v83, v163
	v_mul_f32_e32 v171, v171, v13
	v_add_f32_e32 v175, 1.0, v115
	v_fma_f32 v171, v171, v175, v147
	v_cvt_pk_bf16_f32 v176, v168, v169
	v_cvt_pk_bf16_f32 v177, v170, v171
	v_cvt_pk_bf16_f32 v178, v80, v81
	v_cvt_pk_bf16_f32 v179, v82, v83
	global_store_dwordx2 v8, v[176:177], s[0:1]
	global_store_dwordx2 v8, v[178:179], s[4:5]
	v_mul_f32_e32 v168, v84, v163
	v_mul_f32_e32 v168, v168, v14
	v_add_f32_e32 v172, 1.0, v116
	v_fma_f32 v168, v168, v172, v148
	v_mul_f32_e32 v169, v85, v163
	v_mul_f32_e32 v169, v169, v15
	v_add_f32_e32 v173, 1.0, v117
	v_fma_f32 v169, v169, v173, v149
	v_mul_f32_e32 v170, v86, v163
	v_mul_f32_e32 v170, v170, v16
	v_add_f32_e32 v174, 1.0, v118
	v_fma_f32 v170, v170, v174, v150
	v_mul_f32_e32 v171, v87, v163
	v_mul_f32_e32 v171, v171, v17
	v_add_f32_e32 v175, 1.0, v119
	v_fma_f32 v171, v171, v175, v151
	v_cvt_pk_bf16_f32 v180, v168, v169
	v_cvt_pk_bf16_f32 v181, v170, v171
	v_cvt_pk_bf16_f32 v182, v84, v85
	v_cvt_pk_bf16_f32 v183, v86, v87
	global_store_dwordx2 v8, v[180:181], s[0:1] offset:512
	global_store_dwordx2 v8, v[182:183], s[4:5] offset:512
	v_mul_f32_e32 v168, v88, v163
	v_mul_f32_e32 v168, v168, v18
	v_add_f32_e32 v172, 1.0, v120
	v_fma_f32 v168, v168, v172, v152
	v_mul_f32_e32 v169, v89, v163
	v_mul_f32_e32 v169, v169, v19
	v_add_f32_e32 v173, 1.0, v121
	v_fma_f32 v169, v169, v173, v153
	v_mul_f32_e32 v170, v90, v163
	v_mul_f32_e32 v170, v170, v20
	v_add_f32_e32 v174, 1.0, v122
	v_fma_f32 v170, v170, v174, v154
	v_mul_f32_e32 v171, v91, v163
	v_mul_f32_e32 v171, v171, v21
	v_add_f32_e32 v175, 1.0, v123
	v_fma_f32 v171, v171, v175, v155
	v_cvt_pk_bf16_f32 v184, v168, v169
	v_cvt_pk_bf16_f32 v185, v170, v171
	v_cvt_pk_bf16_f32 v186, v88, v89
	v_cvt_pk_bf16_f32 v187, v90, v91
	global_store_dwordx2 v8, v[184:185], s[0:1] offset:1024
	global_store_dwordx2 v8, v[186:187], s[4:5] offset:1024
	v_mul_f32_e32 v168, v92, v163
	v_mul_f32_e32 v168, v168, v22
	v_add_f32_e32 v172, 1.0, v124
	v_fma_f32 v168, v168, v172, v156
	v_mul_f32_e32 v169, v93, v163
	v_mul_f32_e32 v169, v169, v23
	v_add_f32_e32 v173, 1.0, v125
	v_fma_f32 v169, v169, v173, v157
	v_mul_f32_e32 v170, v94, v163
	v_mul_f32_e32 v170, v170, v24
	v_add_f32_e32 v174, 1.0, v126
	v_fma_f32 v170, v170, v174, v158
	v_mul_f32_e32 v171, v95, v163
	v_mul_f32_e32 v171, v171, v25
	v_add_f32_e32 v175, 1.0, v127
	v_fma_f32 v171, v171, v175, v159
	v_cvt_pk_bf16_f32 v188, v168, v169
	v_cvt_pk_bf16_f32 v189, v170, v171
	v_cvt_pk_bf16_f32 v190, v92, v93
	v_cvt_pk_bf16_f32 v191, v94, v95
	global_store_dwordx2 v8, v[188:189], s[0:1] offset:1536
	global_store_dwordx2 v8, v[190:191], s[4:5] offset:1536
	s_add_u32 s16, s54, 0xc000
	s_addc_u32 s17, s55, 0
	global_load_dwordx4 v[128:131], v1, s[16:17]
	global_load_dwordx4 v[132:135], v1, s[16:17] offset:1024
	global_load_dwordx4 v[136:139], v1, s[16:17] offset:2048
	global_load_dwordx4 v[140:143], v1, s[16:17] offset:3072
	s_add_u32 s16, s16, 0x1000
	s_addc_u32 s17, s17, 0
	global_load_dwordx4 v[96:99], v1, s[16:17]
	global_load_dwordx4 v[100:103], v1, s[16:17] offset:1024
	global_load_dwordx4 v[104:107], v1, s[16:17] offset:2048
	global_load_dwordx4 v[108:111], v1, s[16:17] offset:3072
	s_add_u32 s16, s54, 0x12000
	s_addc_u32 s17, s55, 0
	global_load_dwordx4 v[144:147], v1, s[16:17]
	global_load_dwordx4 v[148:151], v1, s[16:17] offset:1024
	global_load_dwordx4 v[152:155], v1, s[16:17] offset:2048
	global_load_dwordx4 v[156:159], v1, s[16:17] offset:3072
	s_add_u32 s16, s16, 0x1000
	s_addc_u32 s17, s17, 0
	global_load_dwordx4 v[112:115], v1, s[16:17]
	global_load_dwordx4 v[116:119], v1, s[16:17] offset:1024
	global_load_dwordx4 v[120:123], v1, s[16:17] offset:2048
	global_load_dwordx4 v[124:127], v1, s[16:17] offset:3072
	s_waitcnt vmcnt(32)
	v_mul_f32_e32 v166, v32, v32
	v_fmac_f32_e32 v166, v33, v33
	v_mul_f32_e32 v167, v34, v34
	v_fmac_f32_e32 v167, v35, v35
	v_add_f32_e32 v160, v166, v167
	v_mul_f32_e32 v166, v36, v36
	v_fmac_f32_e32 v166, v37, v37
	v_mul_f32_e32 v167, v38, v38
	v_fmac_f32_e32 v167, v39, v39
	v_add_f32_e32 v166, v166, v167
	v_add_f32_e32 v160, v160, v166
	v_mul_f32_e32 v166, v40, v40
	v_fmac_f32_e32 v166, v41, v41
	v_mul_f32_e32 v167, v42, v42
	v_fmac_f32_e32 v167, v43, v43
	v_add_f32_e32 v166, v166, v167
	v_add_f32_e32 v160, v160, v166
	v_mul_f32_e32 v166, v44, v44
	v_fmac_f32_e32 v166, v45, v45
	v_mul_f32_e32 v167, v46, v46
	v_fmac_f32_e32 v167, v47, v47
	v_add_f32_e32 v166, v166, v167
	v_add_f32_e32 v160, v160, v166
	v_mul_f32_e32 v166, v48, v48
	v_fmac_f32_e32 v166, v49, v49
	v_mul_f32_e32 v167, v50, v50
	v_fmac_f32_e32 v167, v51, v51
	v_add_f32_e32 v161, v166, v167
	v_mul_f32_e32 v166, v52, v52
	v_fmac_f32_e32 v166, v53, v53
	v_mul_f32_e32 v167, v54, v54
	v_fmac_f32_e32 v167, v55, v55
	v_add_f32_e32 v166, v166, v167
	v_add_f32_e32 v161, v161, v166
	v_mul_f32_e32 v166, v56, v56
	v_fmac_f32_e32 v166, v57, v57
	v_mul_f32_e32 v167, v58, v58
	v_fmac_f32_e32 v167, v59, v59
	v_add_f32_e32 v166, v166, v167
	v_add_f32_e32 v161, v161, v166
	v_mul_f32_e32 v166, v60, v60
	v_fmac_f32_e32 v166, v61, v61
	v_mul_f32_e32 v167, v62, v62
	v_fmac_f32_e32 v167, v63, v63
	v_add_f32_e32 v166, v166, v167
	v_add_f32_e32 v161, v161, v166
	ds_bpermute_b32 v164, v2, v160
	ds_bpermute_b32 v165, v2, v161
	s_waitcnt lgkmcnt(0)
	v_add_f32_e32 v160, v160, v164
	v_add_f32_e32 v161, v161, v165
	ds_bpermute_b32 v164, v3, v160
	ds_bpermute_b32 v165, v3, v161
	s_waitcnt lgkmcnt(0)
	v_add_f32_e32 v160, v160, v164
	v_add_f32_e32 v161, v161, v165
	ds_bpermute_b32 v164, v4, v160
	ds_bpermute_b32 v165, v4, v161
	s_waitcnt lgkmcnt(0)
	v_add_f32_e32 v160, v160, v164
	v_add_f32_e32 v161, v161, v165
	ds_bpermute_b32 v164, v5, v160
	ds_bpermute_b32 v165, v5, v161
	s_waitcnt lgkmcnt(0)
	v_add_f32_e32 v160, v160, v164
	v_add_f32_e32 v161, v161, v165
	ds_bpermute_b32 v164, v6, v160
	ds_bpermute_b32 v165, v6, v161
	s_waitcnt lgkmcnt(0)
	v_add_f32_e32 v160, v160, v164
	v_add_f32_e32 v161, v161, v165
	ds_bpermute_b32 v164, v7, v160
	ds_bpermute_b32 v165, v7, v161
	s_waitcnt lgkmcnt(0)
	v_add_f32_e32 v160, v160, v164
	v_add_f32_e32 v161, v161, v165
	v_mul_f32_e32 v162, 0x3a800000, v160
	v_add_f32_e32 v162, 0x358637bd, v162
	v_mul_f32_e32 v163, 0x3a800000, v161
	v_add_f32_e32 v163, 0x358637bd, v163
	v_rsq_f32_e32 v162, v162
	v_rsq_f32_e32 v163, v163
	s_waitcnt vmcnt(0)
	s_add_i32 s9, s8, 0x2000
	s_lshl_b32 s9, s9, 11
	s_add_u32 s0, s54, s9
	s_addc_u32 s1, s55, 0
	s_add_u32 s4, s0, 0xda00000
	s_addc_u32 s5, s1, 0
	s_add_u32 s0, s0, 0x4200000
	s_addc_u32 s1, s1, 0
	v_mul_f32_e32 v168, v32, v162
	v_mul_f32_e32 v168, v168, v10
	v_add_f32_e32 v172, 1.0, v96
	v_fma_f32 v168, v168, v172, v128
	v_mul_f32_e32 v169, v33, v162
	v_mul_f32_e32 v169, v169, v11
	v_add_f32_e32 v173, 1.0, v97
	v_fma_f32 v169, v169, v173, v129
	v_mul_f32_e32 v170, v34, v162
	v_mul_f32_e32 v170, v170, v12
	v_add_f32_e32 v174, 1.0, v98
	v_fma_f32 v170, v170, v174, v130
	v_mul_f32_e32 v171, v35, v162
	v_mul_f32_e32 v171, v171, v13
	v_add_f32_e32 v175, 1.0, v99
	v_fma_f32 v171, v171, v175, v131
	v_cvt_pk_bf16_f32 v176, v168, v169
	v_cvt_pk_bf16_f32 v177, v170, v171
	v_cvt_pk_bf16_f32 v178, v32, v33
	v_cvt_pk_bf16_f32 v179, v34, v35
	global_store_dwordx2 v8, v[176:177], s[0:1]
	global_store_dwordx2 v8, v[178:179], s[4:5]
	v_mul_f32_e32 v168, v36, v162
	v_mul_f32_e32 v168, v168, v14
	v_add_f32_e32 v172, 1.0, v100
	v_fma_f32 v168, v168, v172, v132
	v_mul_f32_e32 v169, v37, v162
	v_mul_f32_e32 v169, v169, v15
	v_add_f32_e32 v173, 1.0, v101
	v_fma_f32 v169, v169, v173, v133
	v_mul_f32_e32 v170, v38, v162
	v_mul_f32_e32 v170, v170, v16
	v_add_f32_e32 v174, 1.0, v102
	v_fma_f32 v170, v170, v174, v134
	v_mul_f32_e32 v171, v39, v162
	v_mul_f32_e32 v171, v171, v17
	v_add_f32_e32 v175, 1.0, v103
	v_fma_f32 v171, v171, v175, v135
	v_cvt_pk_bf16_f32 v180, v168, v169
	v_cvt_pk_bf16_f32 v181, v170, v171
	v_cvt_pk_bf16_f32 v182, v36, v37
	v_cvt_pk_bf16_f32 v183, v38, v39
	global_store_dwordx2 v8, v[180:181], s[0:1] offset:512
	global_store_dwordx2 v8, v[182:183], s[4:5] offset:512
	v_mul_f32_e32 v168, v40, v162
	v_mul_f32_e32 v168, v168, v18
	v_add_f32_e32 v172, 1.0, v104
	v_fma_f32 v168, v168, v172, v136
	v_mul_f32_e32 v169, v41, v162
	v_mul_f32_e32 v169, v169, v19
	v_add_f32_e32 v173, 1.0, v105
	v_fma_f32 v169, v169, v173, v137
	v_mul_f32_e32 v170, v42, v162
	v_mul_f32_e32 v170, v170, v20
	v_add_f32_e32 v174, 1.0, v106
	v_fma_f32 v170, v170, v174, v138
	v_mul_f32_e32 v171, v43, v162
	v_mul_f32_e32 v171, v171, v21
	v_add_f32_e32 v175, 1.0, v107
	v_fma_f32 v171, v171, v175, v139
	v_cvt_pk_bf16_f32 v184, v168, v169
	v_cvt_pk_bf16_f32 v185, v170, v171
	v_cvt_pk_bf16_f32 v186, v40, v41
	v_cvt_pk_bf16_f32 v187, v42, v43
	global_store_dwordx2 v8, v[184:185], s[0:1] offset:1024
	global_store_dwordx2 v8, v[186:187], s[4:5] offset:1024
	v_mul_f32_e32 v168, v44, v162
	v_mul_f32_e32 v168, v168, v22
	v_add_f32_e32 v172, 1.0, v108
	v_fma_f32 v168, v168, v172, v140
	v_mul_f32_e32 v169, v45, v162
	v_mul_f32_e32 v169, v169, v23
	v_add_f32_e32 v173, 1.0, v109
	v_fma_f32 v169, v169, v173, v141
	v_mul_f32_e32 v170, v46, v162
	v_mul_f32_e32 v170, v170, v24
	v_add_f32_e32 v174, 1.0, v110
	v_fma_f32 v170, v170, v174, v142
	v_mul_f32_e32 v171, v47, v162
	v_mul_f32_e32 v171, v171, v25
	v_add_f32_e32 v175, 1.0, v111
	v_fma_f32 v171, v171, v175, v143
	v_cvt_pk_bf16_f32 v188, v168, v169
	v_cvt_pk_bf16_f32 v189, v170, v171
	v_cvt_pk_bf16_f32 v190, v44, v45
	v_cvt_pk_bf16_f32 v191, v46, v47
	global_store_dwordx2 v8, v[188:189], s[0:1] offset:1536
	global_store_dwordx2 v8, v[190:191], s[4:5] offset:1536
	s_add_i32 s9, s8, 0x2800
	s_lshl_b32 s9, s9, 11
	s_add_u32 s0, s54, s9
	s_addc_u32 s1, s55, 0
	s_add_u32 s4, s0, 0xda00000
	s_addc_u32 s5, s1, 0
	s_add_u32 s0, s0, 0x4200000
	s_addc_u32 s1, s1, 0
	v_mul_f32_e32 v168, v48, v163
	v_mul_f32_e32 v168, v168, v10
	v_add_f32_e32 v172, 1.0, v112
	v_fma_f32 v168, v168, v172, v144
	v_mul_f32_e32 v169, v49, v163
	v_mul_f32_e32 v169, v169, v11
	v_add_f32_e32 v173, 1.0, v113
	v_fma_f32 v169, v169, v173, v145
	v_mul_f32_e32 v170, v50, v163
	v_mul_f32_e32 v170, v170, v12
	v_add_f32_e32 v174, 1.0, v114
	v_fma_f32 v170, v170, v174, v146
	v_mul_f32_e32 v171, v51, v163
	v_mul_f32_e32 v171, v171, v13
	v_add_f32_e32 v175, 1.0, v115
	v_fma_f32 v171, v171, v175, v147
	v_cvt_pk_bf16_f32 v176, v168, v169
	v_cvt_pk_bf16_f32 v177, v170, v171
	v_cvt_pk_bf16_f32 v178, v48, v49
	v_cvt_pk_bf16_f32 v179, v50, v51
	global_store_dwordx2 v8, v[176:177], s[0:1]
	global_store_dwordx2 v8, v[178:179], s[4:5]
	v_mul_f32_e32 v168, v52, v163
	v_mul_f32_e32 v168, v168, v14
	v_add_f32_e32 v172, 1.0, v116
	v_fma_f32 v168, v168, v172, v148
	v_mul_f32_e32 v169, v53, v163
	v_mul_f32_e32 v169, v169, v15
	v_add_f32_e32 v173, 1.0, v117
	v_fma_f32 v169, v169, v173, v149
	v_mul_f32_e32 v170, v54, v163
	v_mul_f32_e32 v170, v170, v16
	v_add_f32_e32 v174, 1.0, v118
	v_fma_f32 v170, v170, v174, v150
	v_mul_f32_e32 v171, v55, v163
	v_mul_f32_e32 v171, v171, v17
	v_add_f32_e32 v175, 1.0, v119
	v_fma_f32 v171, v171, v175, v151
	v_cvt_pk_bf16_f32 v180, v168, v169
	v_cvt_pk_bf16_f32 v181, v170, v171
	v_cvt_pk_bf16_f32 v182, v52, v53
	v_cvt_pk_bf16_f32 v183, v54, v55
	global_store_dwordx2 v8, v[180:181], s[0:1] offset:512
	global_store_dwordx2 v8, v[182:183], s[4:5] offset:512
	v_mul_f32_e32 v168, v56, v163
	v_mul_f32_e32 v168, v168, v18
	v_add_f32_e32 v172, 1.0, v120
	v_fma_f32 v168, v168, v172, v152
	v_mul_f32_e32 v169, v57, v163
	v_mul_f32_e32 v169, v169, v19
	v_add_f32_e32 v173, 1.0, v121
	v_fma_f32 v169, v169, v173, v153
	v_mul_f32_e32 v170, v58, v163
	v_mul_f32_e32 v170, v170, v20
	v_add_f32_e32 v174, 1.0, v122
	v_fma_f32 v170, v170, v174, v154
	v_mul_f32_e32 v171, v59, v163
	v_mul_f32_e32 v171, v171, v21
	v_add_f32_e32 v175, 1.0, v123
	v_fma_f32 v171, v171, v175, v155
	v_cvt_pk_bf16_f32 v184, v168, v169
	v_cvt_pk_bf16_f32 v185, v170, v171
	v_cvt_pk_bf16_f32 v186, v56, v57
	v_cvt_pk_bf16_f32 v187, v58, v59
	global_store_dwordx2 v8, v[184:185], s[0:1] offset:1024
	global_store_dwordx2 v8, v[186:187], s[4:5] offset:1024
	v_mul_f32_e32 v168, v60, v163
	v_mul_f32_e32 v168, v168, v22
	v_add_f32_e32 v172, 1.0, v124
	v_fma_f32 v168, v168, v172, v156
	v_mul_f32_e32 v169, v61, v163
	v_mul_f32_e32 v169, v169, v23
	v_add_f32_e32 v173, 1.0, v125
	v_fma_f32 v169, v169, v173, v157
	v_mul_f32_e32 v170, v62, v163
	v_mul_f32_e32 v170, v170, v24
	v_add_f32_e32 v174, 1.0, v126
	v_fma_f32 v170, v170, v174, v158
	v_mul_f32_e32 v171, v63, v163
	v_mul_f32_e32 v171, v171, v25
	v_add_f32_e32 v175, 1.0, v127
	v_fma_f32 v171, v171, v175, v159
	v_cvt_pk_bf16_f32 v188, v168, v169
	v_cvt_pk_bf16_f32 v189, v170, v171
	v_cvt_pk_bf16_f32 v190, v60, v61
	v_cvt_pk_bf16_f32 v191, v62, v63
	global_store_dwordx2 v8, v[188:189], s[0:1] offset:1536
	global_store_dwordx2 v8, v[190:191], s[4:5] offset:1536
